# G3 epilogue: 16 residual float4 loads issued up front with counted vmcnt waits (on top of the P1/G2 de-serialisation)
# speedup vs baseline: 1.0212x; 1.0017x over previous
; __device__ __forceinline__ void phase_gemm_out(const Params& p, char* smem) {
;     ...
; #pragma unroll
;     for (int i = 0; i < 4; ++i) {
;       const int m = mt * 128 + wm * 64 + i * 16 + (lane & 15);
; #pragma unroll
;       for (int j = 0; j < 4; ++j) {
;         const int n = nt * 128 + wn * 64 + j * 16 + (lane >> 4) * 4;
;         float4* xp = (float4*)(X + (size_t)m * 1024 + n);
;         float4 x = *xp;
;         x.x += acc[i][j][0]; x.y += acc[i][j][1]; x.z += acc[i][j][2]; x.w += acc[i][j][3];
;         *xp = x;
;       }
;     }
.LBB0_720:
	v_lshl_add_u32 v0, s14, 7, v134
	s_waitcnt vmcnt(7)
	v_lshl_or_b32 v32, s12, 7, v135
	v_ashrrev_i32_e32 v1, 31, v0
	v_ashrrev_i32_e32 v33, 31, v32
	v_lshlrev_b64 v[32:33], 2, v[32:33]
	v_lshlrev_b64 v[34:35], 12, v[0:1]
	v_lshl_add_u64 v[34:35], s[10:11], 0, v[34:35]
	v_lshl_add_u64 v[34:35], v[34:35], 0, v[32:33]
	global_load_dwordx4 v[188:191], v[34:35], off
	global_load_dwordx4 v[192:195], v[34:35], off offset:64
	global_load_dwordx4 v[196:199], v[34:35], off offset:128
	global_load_dwordx4 v[200:203], v[34:35], off offset:192
	v_or_b32_e32 v172, 16, v0
	v_ashrrev_i32_e32 v173, 31, v172
	v_lshlrev_b64 v[172:173], 12, v[172:173]
	v_lshl_add_u64 v[172:173], s[10:11], 0, v[172:173]
	v_lshl_add_u64 v[172:173], v[172:173], 0, v[32:33]
	global_load_dwordx4 v[204:207], v[172:173], off
	global_load_dwordx4 v[208:211], v[172:173], off offset:64
	global_load_dwordx4 v[212:215], v[172:173], off offset:128
	global_load_dwordx4 v[216:219], v[172:173], off offset:192
	v_or_b32_e32 v174, 32, v0
	v_ashrrev_i32_e32 v175, 31, v174
	v_lshlrev_b64 v[174:175], 12, v[174:175]
	v_lshl_add_u64 v[174:175], s[10:11], 0, v[174:175]
	v_lshl_add_u64 v[174:175], v[174:175], 0, v[32:33]
	global_load_dwordx4 v[220:223], v[174:175], off
	global_load_dwordx4 v[224:227], v[174:175], off offset:64
	global_load_dwordx4 v[228:231], v[174:175], off offset:128
	global_load_dwordx4 v[232:235], v[174:175], off offset:192
	v_or_b32_e32 v176, 48, v0
	v_ashrrev_i32_e32 v177, 31, v176
	v_lshlrev_b64 v[176:177], 12, v[176:177]
	v_lshl_add_u64 v[176:177], s[10:11], 0, v[176:177]
	v_lshl_add_u64 v[176:177], v[176:177], 0, v[32:33]
	global_load_dwordx4 v[236:239], v[176:177], off
	global_load_dwordx4 v[160:163], v[176:177], off offset:64
	global_load_dwordx4 v[164:167], v[176:177], off offset:128
	global_load_dwordx4 v[168:171], v[176:177], off offset:192
	s_add_i32 s25, s25, 1
	s_cmp_eq_u32 s25, s23
	s_cselect_b64 s[12:13], -1, 0
	s_waitcnt vmcnt(12)
	v_pk_add_f32 v[188:189], v[96:97], v[188:189]
	v_pk_add_f32 v[190:191], v[98:99], v[190:191]
	v_pk_add_f32 v[192:193], v[92:93], v[192:193]
	v_pk_add_f32 v[194:195], v[94:95], v[194:195]
	v_pk_add_f32 v[196:197], v[88:89], v[196:197]
	v_pk_add_f32 v[198:199], v[90:91], v[198:199]
	v_pk_add_f32 v[200:201], v[84:85], v[200:201]
	v_pk_add_f32 v[202:203], v[86:87], v[202:203]
	global_store_dwordx4 v[34:35], v[188:191], off
	global_store_dwordx4 v[34:35], v[192:195], off offset:64
	global_store_dwordx4 v[34:35], v[196:199], off offset:128
	global_store_dwordx4 v[34:35], v[200:203], off offset:192
	s_waitcnt vmcnt(12)
	v_pk_add_f32 v[204:205], v[80:81], v[204:205]
	v_pk_add_f32 v[206:207], v[82:83], v[206:207]
	v_pk_add_f32 v[208:209], v[76:77], v[208:209]
	v_pk_add_f32 v[210:211], v[78:79], v[210:211]
	v_pk_add_f32 v[212:213], v[72:73], v[212:213]
	v_pk_add_f32 v[214:215], v[74:75], v[214:215]
	v_pk_add_f32 v[216:217], v[60:61], v[216:217]
	v_pk_add_f32 v[218:219], v[62:63], v[218:219]
	global_store_dwordx4 v[172:173], v[204:207], off
	global_store_dwordx4 v[172:173], v[208:211], off offset:64
	global_store_dwordx4 v[172:173], v[212:215], off offset:128
	global_store_dwordx4 v[172:173], v[216:219], off offset:192
	s_waitcnt vmcnt(12)
	v_pk_add_f32 v[220:221], v[36:37], v[220:221]
	v_pk_add_f32 v[222:223], v[38:39], v[222:223]
	v_pk_add_f32 v[224:225], v[28:29], v[224:225]
	v_pk_add_f32 v[226:227], v[30:31], v[226:227]
	v_pk_add_f32 v[228:229], v[24:25], v[228:229]
	v_pk_add_f32 v[230:231], v[26:27], v[230:231]
	v_pk_add_f32 v[232:233], v[20:21], v[232:233]
	v_pk_add_f32 v[234:235], v[22:23], v[234:235]
	global_store_dwordx4 v[174:175], v[220:223], off
	global_store_dwordx4 v[174:175], v[224:227], off offset:64
	global_store_dwordx4 v[174:175], v[228:231], off offset:128
	global_store_dwordx4 v[174:175], v[232:235], off offset:192
	s_waitcnt vmcnt(12)
	v_pk_add_f32 v[236:237], v[16:17], v[236:237]
	v_pk_add_f32 v[238:239], v[18:19], v[238:239]
	v_pk_add_f32 v[160:161], v[12:13], v[160:161]
	v_pk_add_f32 v[162:163], v[14:15], v[162:163]
	v_pk_add_f32 v[164:165], v[8:9], v[164:165]
	v_pk_add_f32 v[166:167], v[10:11], v[166:167]
	v_pk_add_f32 v[168:169], v[4:5], v[168:169]
	v_pk_add_f32 v[170:171], v[6:7], v[170:171]
	global_store_dwordx4 v[176:177], v[236:239], off
	global_store_dwordx4 v[176:177], v[160:163], off offset:64
	global_store_dwordx4 v[176:177], v[164:167], off offset:128
	global_store_dwordx4 v[176:177], v[168:171], off offset:192
